# v12 + attention V staging with 8 lanes per row (full 128-B lines per V load; 4-way LDS write conflicts)
# speedup vs baseline: 1.0104x; 1.0018x over previous
; #define AT_LOADQ(T) do { const size_t tq_ = (T).tb + (size_t)(128 * (T).n + qi) * (T).d; \
;         _Pragma("unroll") for (int k4_ = 0; k4_ < 4; ++k4_) qf[k4_] = *(const bf16x8*)(AQ + tq_ * ATW + (T).head * 128 + k4_ * 32 + 8 * fq); qs = HS[tq_ * 24 + (T).head]; } while (0)
; __device__ __forceinline__ void attn_phase(int wv, const Args& a, LAS unsigned char* lds, int w, bool dmy) {
;     ...
;     const int krow = tid >> 4, kc = tid & 15;
;     const int vc = tid >> 6, vrow = (tid & 63) * 2;
;     const int qi = 16 * wid + fr;
;     u32x4 kr[4], vr[4]; float rk[4]; bf16x8 qf[4]; float qs;
;     ...
;     AttnIt T = attn_decode(12 * w);
;     if (T.n > 0) { AT_LOADBLK(T, T.n - 1); AT_WRITEBLK((T.n & 1) ^ 1); }
;     AT_LOADBLK(T, T.n); AT_LOADQ(T);
.LBB0_646:
	s_or_b64 exec, exec, s[0:1]
	v_readlane_b32 s0, v252, 4
	v_readlane_b32 s1, v252, 5
	s_waitcnt lgkmcnt(0)
	s_barrier
	s_load_dwordx2 s[2:3], s[0:1], 0x88
	v_readlane_b32 s0, v252, 1
	v_mbcnt_lo_u32_b32 v40, -1, 0
	v_mbcnt_hi_u32_b32 v40, -1, v40
	v_readlane_b32 s4, v252, 26
	v_and_b32_e32 v38, 63, v40
	v_or_b32_e32 v39, s0, v40
	s_waitcnt lgkmcnt(0)
	s_add_u32 s0, s2, 0x12100000
	s_addc_u32 s1, s3, 0
	s_add_u32 s13, s2, 0x18100000
	s_addc_u32 s14, s3, 0
	v_ashrrev_i32_e32 v5, 6, v39
	v_and_b32_e32 v85, 15, v40
	s_add_u32 s16, s2, 0x1e100000
	s_waitcnt vmcnt(4)
	v_ashrrev_i32_e32 v89, 4, v39
	v_readlane_b32 s5, v252, 27
	v_readfirstlane_b32 s6, v5
	s_addc_u32 s17, s3, 0
	v_lshrrev_b32_e32 v84, 3, v38
	v_lshlrev_b32_e32 v84, 1, v84
	v_lshl_or_b32 v84, v5, 4, v84
	v_and_b32_e32 v5, 7, v38
	s_and_b64 vcc, exec, s[4:5]
	v_lshlrev_b32_e32 v188, 3, v85
	v_lshlrev_b32_e32 v6, 4, v85
	v_lshlrev_b32_e32 v4, 3, v5
	v_mul_lo_u32 v7, v89, s78
	s_cbranch_vccz .LBB0_648
	v_readlane_b32 s4, v252, 31
	v_readlane_b32 s12, v252, 30
	v_readlane_b32 s5, v252, 32
	s_lshl_b64 s[4:5], s[4:5], 1
	v_add_u32_e32 v16, s12, v89
	s_add_u32 s8, s0, s4
	v_ashrrev_i32_e32 v17, 31, v16
	v_readlane_b32 s7, v252, 23
	v_readlane_b32 s10, v252, 24
	s_addc_u32 s9, s1, s5
	v_lshlrev_b32_e32 v32, 4, v85
	v_mov_b32_e32 v33, v189
	v_lshlrev_b64 v[0:1], s7, v[16:17]
	v_readlane_b32 s11, v252, 25
	v_lshl_add_u64 v[22:23], s[8:9], 0, v[32:33]
	s_add_u32 s8, s13, s4
	v_lshl_add_u64 v[0:1], v[0:1], 0, s[10:11]
	s_addc_u32 s9, s14, s5
	v_mad_u64_u32 v[2:3], s[4:5], v0, s80, v[22:23]
	v_mov_b32_e32 v8, v3
	v_mad_u64_u32 v[8:9], s[4:5], v1, s80, v[8:9]
	v_mov_b32_e32 v3, v8
	v_mov_b64_e32 v[24:25], s[16:17]
	global_load_dwordx4 v[8:11], v[2:3], off
	v_mad_u64_u32 v[2:3], s[4:5], v0, s63, v[24:25]
	v_mov_b32_e32 v0, v3
	v_mad_u64_u32 v[0:1], s[4:5], v1, s63, v[0:1]
	v_readlane_b32 s4, v252, 33
	v_readlane_b32 s5, v252, 34
	v_mov_b32_e32 v3, v0
	s_lshl_b64 s[4:5], s[4:5], 2
	v_lshl_add_u64 v[0:1], v[2:3], 0, s[4:5]
	global_load_dword v33, v[0:1], off offset:48
	v_add_u32_e32 v12, 32, v16
	v_ashrrev_i32_e32 v13, 31, v12
	v_lshlrev_b64 v[12:13], s7, v[12:13]
	v_lshl_add_u64 v[12:13], v[12:13], 0, s[10:11]
	v_or_b32_e32 v18, s12, v84
	v_mov_b32_e32 v19, v189
	v_mov_b64_e32 v[20:21], s[8:9]
	v_mad_u64_u32 v[14:15], s[8:9], v12, s80, v[22:23]
	v_lshlrev_b64 v[0:1], s7, v[18:19]
	v_mov_b32_e32 v30, v15
	v_lshl_add_u64 v[0:1], v[0:1], 0, s[10:11]
	v_mad_u64_u32 v[30:31], s[8:9], v13, s80, v[30:31]
	v_mad_u64_u32 v[2:3], s[8:9], v0, s80, v[20:21]
	v_mov_b32_e32 v15, v30
	v_mad_u64_u32 v[30:31], s[8:9], v12, s63, v[24:25]
	v_mov_b32_e32 v0, v3
	v_lshlrev_b32_e32 v34, 3, v5
	v_mov_b32_e32 v12, v31
	v_mad_u64_u32 v[0:1], s[8:9], v1, s80, v[0:1]
	v_ashrrev_i32_e32 v35, 31, v34
	v_mad_u64_u32 v[12:13], s[8:9], v13, s63, v[12:13]
	v_or_b32_e32 v18, 1, v18
	v_mov_b32_e32 v3, v0
	v_lshlrev_b64 v[26:27], 1, v[34:35]
	v_mov_b32_e32 v31, v12
	v_lshlrev_b64 v[18:19], s7, v[18:19]
	v_lshl_add_u64 v[28:29], v[2:3], 0, v[26:27]
	v_lshl_add_u64 v[12:13], v[30:31], 0, s[4:5]
	v_lshl_add_u64 v[18:19], v[18:19], 0, s[10:11]
	global_load_dwordx4 v[0:3], v[28:29], off
	global_load_dword v41, v[12:13], off offset:48
	s_nop 0
	global_load_dwordx4 v[12:15], v[14:15], off
	v_mad_u64_u32 v[30:31], s[8:9], v18, s80, v[20:21]
	v_mov_b32_e32 v18, v31
	v_mad_u64_u32 v[36:37], s[8:9], v19, s80, v[18:19]
	v_add_u32_e32 v18, 64, v16
	v_ashrrev_i32_e32 v19, 31, v18
	v_lshlrev_b64 v[18:19], s7, v[18:19]
	v_lshl_add_u64 v[18:19], v[18:19], 0, s[10:11]
	v_mad_u64_u32 v[42:43], s[8:9], v18, s63, v[24:25]
	v_mad_u64_u32 v[20:21], s[8:9], v18, s80, v[22:23]
	v_mov_b32_e32 v18, v43
	v_mad_u64_u32 v[44:45], s[8:9], v19, s63, v[18:19]
	v_mov_b32_e32 v43, v44
	v_lshl_add_u64 v[42:43], v[42:43], 0, s[4:5]
	global_load_dword v50, v[42:43], off offset:48
	v_add_u32_e32 v16, 0x60, v16
	v_mov_b32_e32 v18, v21
	v_ashrrev_i32_e32 v17, 31, v16
	v_mad_u64_u32 v[18:19], s[8:9], v19, s80, v[18:19]
	v_lshlrev_b64 v[16:17], s7, v[16:17]
	v_mov_b32_e32 v21, v18
	v_lshl_add_u64 v[16:17], v[16:17], 0, s[10:11]
	global_load_dwordx4 v[18:21], v[20:21], off
	v_mad_u64_u32 v[22:23], s[8:9], v16, s80, v[22:23]
	v_mad_u64_u32 v[24:25], s[8:9], v16, s63, v[24:25]
	v_mov_b32_e32 v42, v23
	v_mov_b32_e32 v16, v25
	v_mad_u64_u32 v[42:43], s[8:9], v17, s80, v[42:43]
	v_mad_u64_u32 v[16:17], s[8:9], v17, s63, v[16:17]
	v_mov_b32_e32 v23, v42
	v_mov_b32_e32 v25, v16
	v_lshl_add_u64 v[16:17], v[24:25], 0, s[4:5]
	global_load_dwordx4 v[22:25], v[22:23], off
	s_nop 0
	global_load_dword v51, v[16:17], off offset:48
	v_mov_b32_e32 v31, v36
	v_lshl_add_u64 v[30:31], v[30:31], 0, v[26:27]
	s_waitcnt vmcnt(7)
	v_fmamk_f32 v26, v33, 0x3c000000, v226
	v_mul_f32_e32 v27, 0x4b800000, v26
	v_cmp_gt_f32_e32 vcc, s33, v26
	v_lshlrev_b32_e32 v36, 16, v8
	v_and_b32_e32 v37, 0xffff0000, v8
	v_cndmask_b32_e32 v26, v26, v27, vcc
	v_rsq_f32_e32 v33, v26
	global_load_dwordx4 v[26:29], v[28:29], off offset:128
	s_nop 0
	global_load_dwordx4 v[42:45], v[30:31], off
	global_load_dwordx4 v[46:49], v[30:31], off offset:128
	s_movk_i32 s4, 0x840
	v_add_u32_e32 v16, 64, v34
	v_mul_f32_e32 v30, 0x45800000, v33
	v_cndmask_b32_e32 v30, v33, v30, vcc
	v_pk_mul_f32 v[36:37], v[30:31], v[36:37] op_sel_hi:[0,1]
	v_cvt_pk_bf16_f32 v8, v36, v37
	v_lshlrev_b32_e32 v36, 16, v9
	v_and_b32_e32 v37, 0xffff0000, v9
	v_pk_mul_f32 v[36:37], v[30:31], v[36:37] op_sel_hi:[0,1]
	v_cvt_pk_bf16_f32 v9, v36, v37
	v_lshlrev_b32_e32 v36, 16, v10
	v_and_b32_e32 v37, 0xffff0000, v10
	v_pk_mul_f32 v[36:37], v[30:31], v[36:37] op_sel_hi:[0,1]
	v_cvt_pk_bf16_f32 v10, v36, v37
	v_lshlrev_b32_e32 v36, 16, v11
	v_and_b32_e32 v37, 0xffff0000, v11
	v_pk_mul_f32 v[30:31], v[30:31], v[36:37] op_sel_hi:[0,1]
	v_cvt_pk_bf16_f32 v11, v30, v31
	v_mul_lo_u32 v33, v89, s78
	v_ashrrev_i32_e32 v17, 31, v16
	s_waitcnt vmcnt(8)
; __device__ __forceinline__ void attn_phase(int wv, const Args& a, LAS unsigned char* lds, int w, bool dmy) {
;     ...
;     AttnIt T = attn_decode(12 * w);
;     if (T.n > 0) { AT_LOADBLK(T, T.n - 1); AT_WRITEBLK((T.n & 1) ^ 1); }
	v_fmamk_f32 v30, v41, 0x3c000000, v226
	v_mul_f32_e32 v31, 0x4b800000, v30
	v_cmp_gt_f32_e32 vcc, s33, v30
	v_add_u32_e32 v41, 0x8800, v33
	s_nop 0
	v_cndmask_b32_e32 v30, v30, v31, vcc
	v_rsq_f32_e32 v30, v30
	v_add3_u32 v31, 0, v32, v33
	ds_write_b128 v31, v[8:11] offset:34816
	s_waitcnt vmcnt(7)
	v_and_b32_e32 v9, 0xffff0000, v12
	v_mul_f32_e32 v8, 0x45800000, v30
	v_cndmask_b32_e32 v30, v30, v8, vcc
	v_lshlrev_b32_e32 v8, 16, v12
	v_lshlrev_b32_e32 v10, 16, v13
	v_and_b32_e32 v11, 0xffff0000, v13
	v_pk_mul_f32 v[8:9], v[30:31], v[8:9] op_sel_hi:[0,1]
	v_pk_mul_f32 v[10:11], v[30:31], v[10:11] op_sel_hi:[0,1]
	v_cvt_pk_bf16_f32 v8, v8, v9
	v_cvt_pk_bf16_f32 v9, v10, v11
	v_lshlrev_b32_e32 v10, 16, v14
	v_and_b32_e32 v11, 0xffff0000, v14
	v_pk_mul_f32 v[10:11], v[30:31], v[10:11] op_sel_hi:[0,1]
	v_cvt_pk_bf16_f32 v10, v10, v11
	s_waitcnt vmcnt(6)
	v_fmamk_f32 v11, v50, 0x3c000000, v226
	v_mul_f32_e32 v14, 0x4b800000, v11
	v_cmp_gt_f32_e32 vcc, s33, v11
	v_lshlrev_b32_e32 v12, 16, v15
	v_and_b32_e32 v13, 0xffff0000, v15
	v_cndmask_b32_e32 v11, v11, v14, vcc
	v_rsq_f32_e32 v14, v11
	v_pk_mul_f32 v[12:13], v[30:31], v[12:13] op_sel_hi:[0,1]
	v_cvt_pk_bf16_f32 v11, v12, v13
	ds_write_b128 v31, v[8:11] offset:43520
	v_mul_f32_e32 v8, 0x45800000, v14
	v_cndmask_b32_e32 v12, v14, v8, vcc
	s_waitcnt vmcnt(5)
	v_lshlrev_b32_e32 v8, 16, v18
	v_and_b32_e32 v9, 0xffff0000, v18
	v_lshlrev_b32_e32 v10, 16, v19
	v_and_b32_e32 v11, 0xffff0000, v19
	v_pk_mul_f32 v[8:9], v[12:13], v[8:9] op_sel_hi:[0,1]
	v_pk_mul_f32 v[10:11], v[12:13], v[10:11] op_sel_hi:[0,1]
	v_cvt_pk_bf16_f32 v8, v8, v9
	v_cvt_pk_bf16_f32 v9, v10, v11
	v_lshlrev_b32_e32 v10, 16, v20
	v_and_b32_e32 v11, 0xffff0000, v20
	v_pk_mul_f32 v[10:11], v[12:13], v[10:11] op_sel_hi:[0,1]
	v_cvt_pk_bf16_f32 v10, v10, v11
	s_waitcnt vmcnt(3)
	v_fmamk_f32 v11, v51, 0x3c000000, v226
	v_mul_f32_e32 v13, 0x4b800000, v11
	v_cmp_gt_f32_e32 vcc, s33, v11
	v_lshlrev_b32_e32 v14, 16, v21
	v_and_b32_e32 v15, 0xffff0000, v21
	v_cndmask_b32_e32 v11, v11, v13, vcc
	v_rsq_f32_e32 v18, v11
	v_pk_mul_f32 v[12:13], v[12:13], v[14:15] op_sel_hi:[0,1]
	v_cvt_pk_bf16_f32 v11, v12, v13
	ds_write_b128 v31, v[8:11] offset:52224
	v_mul_f32_e32 v8, 0x45800000, v18
	v_cndmask_b32_e32 v12, v18, v8, vcc
	v_lshlrev_b32_e32 v8, 16, v22
	v_and_b32_e32 v9, 0xffff0000, v22
	v_lshlrev_b32_e32 v10, 16, v23
	v_and_b32_e32 v11, 0xffff0000, v23
	v_pk_mul_f32 v[8:9], v[12:13], v[8:9] op_sel_hi:[0,1]
	v_pk_mul_f32 v[10:11], v[12:13], v[10:11] op_sel_hi:[0,1]
	v_cvt_pk_bf16_f32 v8, v8, v9
	v_cvt_pk_bf16_f32 v9, v10, v11
	v_lshlrev_b32_e32 v10, 16, v24
	v_and_b32_e32 v11, 0xffff0000, v24
	v_lshlrev_b32_e32 v14, 16, v25
	v_and_b32_e32 v15, 0xffff0000, v25
	v_pk_mul_f32 v[10:11], v[12:13], v[10:11] op_sel_hi:[0,1]
	v_pk_mul_f32 v[12:13], v[12:13], v[14:15] op_sel_hi:[0,1]
	v_cvt_pk_bf16_f32 v10, v10, v11
	v_cvt_pk_bf16_f32 v11, v12, v13
	ds_write_b128 v31, v[8:11] offset:60928
	v_mad_u64_u32 v[8:9], s[4:5], v5, s4, v[84:85]
	v_lshl_add_u32 v5, v8, 1, 0
	v_and_b32_e32 v8, 0xffff, v0
	v_lshrrev_b32_e32 v0, 16, v0
	s_mov_b32 s4, 0xffff0000
	v_add_u32_e32 v5, 0x11100, v5
	s_waitcnt vmcnt(1)
	v_lshl_or_b32 v8, v42, 16, v8
	v_and_or_b32 v0, v42, s4, v0
	ds_write2_b32 v5, v8, v0 offset1:132
	v_and_b32_e32 v0, 0xffff, v1
	v_lshrrev_b32_e32 v1, 16, v1
	v_lshl_or_b32 v0, v43, 16, v0
	v_and_or_b32 v1, v43, s4, v1
	v_add_u32_e32 v8, 0x400, v5
	ds_write2_b32 v8, v0, v1 offset0:8 offset1:140
	v_and_b32_e32 v0, 0xffff, v2
	v_lshrrev_b32_e32 v1, 16, v2
	v_lshl_or_b32 v0, v44, 16, v0
	v_and_or_b32 v1, v44, s4, v1
	v_add_u32_e32 v2, 0x800, v5
	ds_write2_b32 v2, v0, v1 offset0:16 offset1:148
	v_and_b32_e32 v0, 0xffff, v3
	v_lshrrev_b32_e32 v1, 16, v3
	v_lshl_or_b32 v0, v45, 16, v0
	v_and_or_b32 v1, v45, s4, v1
	v_add_u32_e32 v2, 0xc00, v5
	ds_write2_b32 v2, v0, v1 offset0:24 offset1:156
	v_and_b32_e32 v0, 0xffff, v26
	v_lshrrev_b32_e32 v1, 16, v26
	s_waitcnt vmcnt(0)
	v_lshl_or_b32 v0, v46, 16, v0
	v_and_or_b32 v1, v46, s4, v1
	v_add_u32_e32 v2, 0x8400, v5
	ds_write2_b32 v2, v0, v1 offset1:132
	v_and_b32_e32 v0, 0xffff, v27
	v_lshrrev_b32_e32 v1, 16, v27
	v_lshl_or_b32 v0, v47, 16, v0
	v_and_or_b32 v1, v47, s4, v1
	v_add_u32_e32 v2, 0x8800, v5
	ds_write2_b32 v2, v0, v1 offset0:8 offset1:140
	v_and_b32_e32 v0, 0xffff, v28
	v_lshrrev_b32_e32 v1, 16, v28
	v_lshl_or_b32 v0, v48, 16, v0
	v_and_or_b32 v1, v48, s4, v1
	v_add_u32_e32 v2, 0x8c00, v5
	ds_write2_b32 v2, v0, v1 offset0:16 offset1:148
	v_and_b32_e32 v0, 0xffff, v29
	v_lshrrev_b32_e32 v1, 16, v29
	v_lshl_or_b32 v0, v49, 16, v0
	v_and_or_b32 v1, v49, s4, v1
	v_add_u32_e32 v2, 0x9000, v5
	ds_write2_b32 v2, v0, v1 offset0:24 offset1:156
	s_mov_b64 s[4:5], 0
	v_mov_b64_e32 v[0:1], v[34:35]
	s_branch .LBB0_649
